# v40: v39 + residual GEMM epilogue: five of the second row-half's residual quads are loaded at the top of the epilogue (dead fragment registers) instead of behind the first half's stores
# baseline (speedup 1.0000x reference)
.LBB0_101:
	s_and_b64 vcc, exec, s[40:41]
	v_readlane_b32 s33, v245, 29
	s_cbranch_vccz .LBB0_119
	v_ashrrev_i32_e32 v167, 31, v166
	v_cmp_lt_i32_e32 vcc, v209, v204
	v_lshlrev_b64 v[200:201], 1, v[166:167]
	v_ashrrev_i32_e32 v169, 31, v168
	v_cndmask_b32_e32 v128, v202, v209, vcc
	v_cmp_lt_i32_e32 vcc, v210, v204
	v_lshlrev_b32_e32 v190, 2, v128
	v_lshl_add_u64 v[170:171], s[16:17], 0, v[200:201]
	v_cndmask_b32_e32 v128, v202, v210, vcc
	v_lshlrev_b64 v[218:219], 11, v[168:169]
	v_lshlrev_b32_e32 v189, 2, v128
	v_lshl_add_u64 v[128:129], v[170:171], 0, v[218:219]
	global_load_dwordx4 v[214:217], v[128:129], off
	global_load_dwordx4 v[152:155], v[128:129], off offset:256
	v_or_b32_e32 v180, 16, v168
	v_ashrrev_i32_e32 v181, 31, v180
	v_or_b32_e32 v176, 32, v168
	v_lshlrev_b64 v[182:183], 11, v[180:181]
	v_ashrrev_i32_e32 v177, 31, v176
	v_or_b32_e32 v172, 48, v168
	v_lshl_add_u64 v[128:129], v[170:171], 0, v[182:183]
	v_lshlrev_b64 v[178:179], 11, v[176:177]
	v_ashrrev_i32_e32 v173, 31, v172
	global_load_dwordx4 v[148:151], v[128:129], off
	global_load_dwordx4 v[144:147], v[128:129], off offset:256
	v_lshl_add_u64 v[128:129], v[170:171], 0, v[178:179]
	v_lshlrev_b64 v[174:175], 11, v[172:173]
	global_load_dwordx4 v[140:143], v[128:129], off
	global_load_dwordx4 v[136:139], v[128:129], off offset:256
	v_lshl_add_u64 v[128:129], v[170:171], 0, v[174:175]
	global_load_dwordx4 v[132:135], v[128:129], off
	s_nop 0
	global_load_dwordx4 v[128:131], v[128:129], off offset:256
	v_add_u32_e32 v242, 0x80, v168
	v_ashrrev_i32_e32 v243, 31, v242
	v_lshlrev_b64 v[242:243], 11, v[242:243]
	v_lshl_add_u64 v[250:251], v[170:171], 0, v[242:243]
	global_load_dwordx4 v[222:225], v[250:251], off
	global_load_dwordx4 v[226:229], v[250:251], off offset:256
	v_add_u32_e32 v242, 0x90, v168
	v_ashrrev_i32_e32 v243, 31, v242
	v_lshlrev_b64 v[242:243], 11, v[242:243]
	v_lshl_add_u64 v[250:251], v[170:171], 0, v[242:243]
	global_load_dwordx4 v[230:233], v[250:251], off
	global_load_dwordx4 v[234:237], v[250:251], off offset:256
	v_add_u32_e32 v242, 0xa0, v168
	v_ashrrev_i32_e32 v243, 31, v242
	v_lshlrev_b64 v[242:243], 11, v[242:243]
	v_lshl_add_u64 v[250:251], v[170:171], 0, v[242:243]
	global_load_dwordx4 v[238:241], v[250:251], off
	v_lshl_add_u64 v[218:219], s[16:17], 0, v[218:219]
	v_lshl_add_u64 v[200:201], v[218:219], 0, v[200:201]
	s_waitcnt vmcnt(5)
	v_lshlrev_b32_e32 v220, 16, v214
	v_and_b32_e32 v221, 0xffff0000, v214
	v_lshlrev_b32_e32 v214, 16, v215
	v_and_b32_e32 v215, 0xffff0000, v215
	v_pk_add_f32 v[126:127], v[126:127], v[214:215]
	v_lshlrev_b32_e32 v214, 16, v216
	v_and_b32_e32 v215, 0xffff0000, v216
	v_lshlrev_b32_e32 v216, 16, v217
	v_and_b32_e32 v217, 0xffff0000, v217
	v_pk_add_f32 v[124:125], v[124:125], v[220:221]
	v_pk_add_f32 v[216:217], v[122:123], v[216:217]
	v_pk_add_f32 v[214:215], v[120:121], v[214:215]
	v_cvt_pk_bf16_f32 v120, v124, v125
	v_cvt_pk_bf16_f32 v121, v126, v127
	v_cvt_pk_bf16_f32 v122, v214, v215
	v_cvt_pk_bf16_f32 v123, v216, v217
	global_store_dwordx4 v[200:201], v[120:123], off
	s_nop 1
	v_mul_f32_e32 v120, v125, v125
	v_mul_f32_e32 v121, v127, v127
	v_fmac_f32_e32 v120, v124, v124
	v_fmac_f32_e32 v121, v126, v126
	v_add_f32_e32 v120, v120, v121
	v_mul_f32_e32 v121, v215, v215
	v_fmac_f32_e32 v121, v214, v214
	v_add_f32_e32 v120, v121, v120
	v_mul_f32_e32 v121, v217, v217
	v_fmac_f32_e32 v121, v216, v216
	v_add_f32_e32 v124, v121, v120
	v_lshlrev_b32_e32 v120, 16, v152
	v_and_b32_e32 v121, 0xffff0000, v152
	v_lshlrev_b32_e32 v122, 16, v153
	v_and_b32_e32 v123, 0xffff0000, v153
	v_pk_add_f32 v[118:119], v[118:119], v[122:123]
	v_pk_add_f32 v[116:117], v[116:117], v[120:121]
	v_lshlrev_b32_e32 v120, 16, v154
	v_and_b32_e32 v121, 0xffff0000, v154
	v_lshlrev_b32_e32 v122, 16, v155
	v_and_b32_e32 v123, 0xffff0000, v155
	v_pk_add_f32 v[122:123], v[114:115], v[122:123]
	v_pk_add_f32 v[120:121], v[112:113], v[120:121]
	v_cvt_pk_bf16_f32 v112, v116, v117
	v_cvt_pk_bf16_f32 v113, v118, v119
	v_cvt_pk_bf16_f32 v114, v120, v121
	v_cvt_pk_bf16_f32 v115, v122, v123
	global_store_dwordx4 v[200:201], v[112:115], off offset:256
	s_nop 1
	v_mul_f32_e32 v112, v117, v117
	v_mul_f32_e32 v113, v119, v119
	v_fmac_f32_e32 v112, v116, v116
	v_fmac_f32_e32 v113, v118, v118
	v_add_f32_e32 v112, v112, v113
	v_mul_f32_e32 v113, v121, v121
	v_fmac_f32_e32 v113, v120, v120
	v_add_f32_e32 v112, v113, v112
	v_mul_f32_e32 v113, v123, v123
	v_fmac_f32_e32 v113, v122, v122
	v_add_f32_e32 v112, v113, v112
	v_add_f32_e32 v112, v124, v112
	ds_bpermute_b32 v113, v190, v112
	s_waitcnt lgkmcnt(0)
	v_add_f32_e32 v112, v112, v113
	ds_bpermute_b32 v113, v189, v112
	s_and_saveexec_b64 s[40:41], s[36:37]
	s_cbranch_execz .LBB0_104
	s_waitcnt lgkmcnt(0)
	v_add_f32_e32 v114, v112, v113
	v_lshlrev_b64 v[112:113], 6, v[168:169]
	s_lshl_b32 s42, s26, 2
	v_lshl_add_u64 v[112:113], s[10:11], 0, v[112:113]
	s_ashr_i32 s43, s42, 31
	v_lshl_add_u64 v[112:113], s[42:43], 2, v[112:113]
	s_lshl_b32 s42, s77, 2
	s_mov_b32 s43, s4
	v_lshl_add_u64 v[112:113], v[112:113], 0, s[42:43]
	global_store_dword v[112:113], v114, off

.LBB0_110:
	s_or_b64 exec, exec, s[40:41]
	v_add_u32_e32 v104, 0x80, v168
	v_ashrrev_i32_e32 v105, 31, v104
	v_lshlrev_b64 v[110:111], 11, v[104:105]
	s_waitcnt lgkmcnt(0)
	v_lshl_add_u64 v[64:65], v[170:171], 0, v[110:111]
	v_add_u32_e32 v100, 0x90, v168
	v_ashrrev_i32_e32 v101, 31, v100
	v_add_u32_e32 v96, 0xa0, v168
	v_lshlrev_b64 v[102:103], 11, v[100:101]
	v_ashrrev_i32_e32 v97, 31, v96
	v_add_u32_e32 v92, 0xb0, v168
	v_lshl_add_u64 v[64:65], v[170:171], 0, v[102:103]
	v_lshlrev_b64 v[98:99], 11, v[96:97]
	v_ashrrev_i32_e32 v93, 31, v92
	v_lshl_add_u64 v[64:65], v[170:171], 0, v[98:99]
	v_lshlrev_b64 v[94:95], 11, v[92:93]
	global_load_dwordx4 v[72:75], v[64:65], off offset:256
	v_lshl_add_u64 v[64:65], v[170:171], 0, v[94:95]
	global_load_dwordx4 v[68:71], v[64:65], off
	s_nop 0
	global_load_dwordx4 v[64:67], v[64:65], off offset:256
	v_lshl_add_u64 v[110:111], s[16:17], 0, v[110:111]
	v_lshl_add_u64 v[110:111], v[166:167], 1, v[110:111]
	s_waitcnt vmcnt(11)
	v_mov_b32_e32 v106, v222
	v_mov_b32_e32 v107, v223
	v_mov_b32_e32 v108, v224
	v_mov_b32_e32 v109, v225
	v_mov_b32_e32 v88, v226
	v_mov_b32_e32 v89, v227
	v_mov_b32_e32 v90, v228
	v_mov_b32_e32 v91, v229
	v_mov_b32_e32 v84, v230
	v_mov_b32_e32 v85, v231
	v_mov_b32_e32 v86, v232
	v_mov_b32_e32 v87, v233
	v_mov_b32_e32 v80, v234
	v_mov_b32_e32 v81, v235
	v_mov_b32_e32 v82, v236
	v_mov_b32_e32 v83, v237
	v_mov_b32_e32 v76, v238
	v_mov_b32_e32 v77, v239
	v_mov_b32_e32 v78, v240
	v_mov_b32_e32 v79, v241
	v_lshlrev_b32_e32 v112, 16, v106
	v_and_b32_e32 v113, 0xffff0000, v106
	v_lshlrev_b32_e32 v106, 16, v107
	v_and_b32_e32 v107, 0xffff0000, v107
	v_pk_add_f32 v[62:63], v[62:63], v[106:107]
	v_lshlrev_b32_e32 v106, 16, v108
	v_and_b32_e32 v107, 0xffff0000, v108
	v_lshlrev_b32_e32 v108, 16, v109
	v_and_b32_e32 v109, 0xffff0000, v109
	v_pk_add_f32 v[60:61], v[60:61], v[112:113]
	v_pk_add_f32 v[108:109], v[58:59], v[108:109]
	v_pk_add_f32 v[106:107], v[56:57], v[106:107]
	v_cvt_pk_bf16_f32 v56, v60, v61
	v_cvt_pk_bf16_f32 v57, v62, v63
	v_cvt_pk_bf16_f32 v58, v106, v107
	v_cvt_pk_bf16_f32 v59, v108, v109
	global_store_dwordx4 v[110:111], v[56:59], off
	s_nop 1
	v_mul_f32_e32 v56, v61, v61
	v_mul_f32_e32 v57, v63, v63
	v_fmac_f32_e32 v56, v60, v60
	v_fmac_f32_e32 v57, v62, v62
	v_add_f32_e32 v56, v56, v57
	v_mul_f32_e32 v57, v107, v107
	v_fmac_f32_e32 v57, v106, v106
	v_add_f32_e32 v56, v57, v56
	v_mul_f32_e32 v57, v109, v109
	v_fmac_f32_e32 v57, v108, v108
	v_add_f32_e32 v60, v57, v56
	v_lshlrev_b32_e32 v56, 16, v88
	v_and_b32_e32 v57, 0xffff0000, v88
	v_lshlrev_b32_e32 v58, 16, v89
	v_and_b32_e32 v59, 0xffff0000, v89
	v_pk_add_f32 v[54:55], v[54:55], v[58:59]
	v_pk_add_f32 v[52:53], v[52:53], v[56:57]
	v_lshlrev_b32_e32 v56, 16, v90
	v_and_b32_e32 v57, 0xffff0000, v90
	v_lshlrev_b32_e32 v58, 16, v91
	v_and_b32_e32 v59, 0xffff0000, v91
	v_pk_add_f32 v[58:59], v[50:51], v[58:59]
	v_pk_add_f32 v[56:57], v[48:49], v[56:57]
	v_cvt_pk_bf16_f32 v48, v52, v53
	v_cvt_pk_bf16_f32 v49, v54, v55
	v_cvt_pk_bf16_f32 v50, v56, v57
	v_cvt_pk_bf16_f32 v51, v58, v59
	global_store_dwordx4 v[110:111], v[48:51], off offset:256
	s_nop 1
	v_mul_f32_e32 v48, v53, v53
	v_mul_f32_e32 v49, v55, v55
	v_fmac_f32_e32 v48, v52, v52
	v_fmac_f32_e32 v49, v54, v54
	v_add_f32_e32 v48, v48, v49
	v_mul_f32_e32 v49, v57, v57
	v_fmac_f32_e32 v49, v56, v56
	v_add_f32_e32 v48, v49, v48
	v_mul_f32_e32 v49, v59, v59
	v_fmac_f32_e32 v49, v58, v58
	v_add_f32_e32 v48, v49, v48
	v_add_f32_e32 v48, v60, v48
	ds_bpermute_b32 v49, v190, v48
	s_waitcnt lgkmcnt(0)
	v_add_f32_e32 v48, v48, v49
	ds_bpermute_b32 v49, v189, v48
	s_and_saveexec_b64 s[40:41], s[36:37]
	s_cbranch_execz .LBB0_112
	s_waitcnt lgkmcnt(0)
	v_add_f32_e32 v50, v48, v49
	v_lshlrev_b64 v[48:49], 6, v[104:105]
	s_lshl_b32 s42, s26, 2
	v_lshl_add_u64 v[48:49], s[10:11], 0, v[48:49]
	s_ashr_i32 s43, s42, 31
	v_lshl_add_u64 v[48:49], s[42:43], 2, v[48:49]
	s_lshl_b32 s42, s77, 2
	s_mov_b32 s43, s4
	v_lshl_add_u64 v[48:49], v[48:49], 0, s[42:43]
	global_store_dword v[48:49], v50, off
.LBB0_112:
	s_or_b64 exec, exec, s[40:41]
	v_lshlrev_b32_e32 v48, 16, v84
	s_waitcnt lgkmcnt(0)
	v_and_b32_e32 v49, 0xffff0000, v84
	v_lshlrev_b32_e32 v50, 16, v85
	v_and_b32_e32 v51, 0xffff0000, v85
	v_pk_add_f32 v[44:45], v[44:45], v[48:49]
	v_lshlrev_b32_e32 v48, 16, v86
	v_and_b32_e32 v49, 0xffff0000, v86
	v_pk_add_f32 v[46:47], v[46:47], v[50:51]
	v_pk_add_f32 v[48:49], v[40:41], v[48:49]
	v_cvt_pk_bf16_f32 v40, v44, v45
	v_mul_f32_e32 v45, v45, v45
	v_fmac_f32_e32 v45, v44, v44
	v_mul_f32_e32 v44, v47, v47
	v_fmac_f32_e32 v44, v46, v46
	v_lshlrev_b32_e32 v50, 16, v87
	v_and_b32_e32 v51, 0xffff0000, v87
	v_add_f32_e32 v44, v45, v44
	v_mul_f32_e32 v45, v49, v49
	v_pk_add_f32 v[50:51], v[42:43], v[50:51]
	v_fmac_f32_e32 v45, v48, v48
	v_add_f32_e32 v44, v45, v44
	v_mul_f32_e32 v45, v51, v51
	v_fmac_f32_e32 v45, v50, v50
	v_cvt_pk_bf16_f32 v41, v46, v47
	v_cvt_pk_bf16_f32 v42, v48, v49
	v_add_f32_e32 v48, v45, v44
	v_lshlrev_b32_e32 v44, 16, v80
	v_and_b32_e32 v45, 0xffff0000, v80
	v_lshlrev_b32_e32 v46, 16, v81
	v_and_b32_e32 v47, 0xffff0000, v81
	v_pk_add_f32 v[38:39], v[38:39], v[46:47]
	v_pk_add_f32 v[36:37], v[36:37], v[44:45]
	v_lshlrev_b32_e32 v44, 16, v82
	v_and_b32_e32 v45, 0xffff0000, v82
	v_pk_add_f32 v[44:45], v[32:33], v[44:45]
	v_mul_f32_e32 v32, v37, v37
	v_mul_f32_e32 v33, v39, v39
	v_fmac_f32_e32 v32, v36, v36
	v_fmac_f32_e32 v33, v38, v38
	v_lshlrev_b32_e32 v46, 16, v83
	v_and_b32_e32 v47, 0xffff0000, v83
	v_add_f32_e32 v32, v32, v33
	v_mul_f32_e32 v33, v45, v45
	v_pk_add_f32 v[46:47], v[34:35], v[46:47]
	v_fmac_f32_e32 v33, v44, v44
	v_add_f32_e32 v32, v33, v32
	v_mul_f32_e32 v33, v47, v47
	v_fmac_f32_e32 v33, v46, v46
	v_add_f32_e32 v32, v33, v32
	v_add_f32_e32 v35, v48, v32
	v_cvt_pk_bf16_f32 v43, v50, v51
	ds_bpermute_b32 v50, v190, v35
	v_lshl_add_u64 v[32:33], s[16:17], 0, v[102:103]
	v_lshl_add_u64 v[48:49], v[166:167], 1, v[32:33]
	v_cvt_pk_bf16_f32 v34, v36, v37
	v_cvt_pk_bf16_f32 v36, v44, v45
	s_waitcnt lgkmcnt(0)
	v_add_f32_e32 v32, v35, v50
	ds_bpermute_b32 v33, v189, v32
	v_cvt_pk_bf16_f32 v35, v38, v39
	v_cvt_pk_bf16_f32 v37, v46, v47
	global_store_dwordx4 v[48:49], v[40:43], off
	global_store_dwordx4 v[48:49], v[34:37], off offset:256
	s_and_saveexec_b64 s[40:41], s[36:37]
	s_cbranch_execz .LBB0_114
	s_waitcnt lgkmcnt(0)
	v_add_f32_e32 v34, v32, v33
	v_lshlrev_b64 v[32:33], 6, v[100:101]
	s_lshl_b32 s42, s26, 2
	v_lshl_add_u64 v[32:33], s[10:11], 0, v[32:33]
	s_ashr_i32 s43, s42, 31
	v_lshl_add_u64 v[32:33], s[42:43], 2, v[32:33]
	s_lshl_b32 s42, s77, 2
	s_mov_b32 s43, s4
	v_lshl_add_u64 v[32:33], v[32:33], 0, s[42:43]
	global_store_dword v[32:33], v34, off
.LBB0_114:
	s_or_b64 exec, exec, s[40:41]
	v_lshlrev_b32_e32 v32, 16, v76
	s_waitcnt lgkmcnt(0)
	v_and_b32_e32 v33, 0xffff0000, v76
	v_lshlrev_b32_e32 v34, 16, v77
	v_and_b32_e32 v35, 0xffff0000, v77
	v_pk_add_f32 v[28:29], v[28:29], v[32:33]
	v_lshlrev_b32_e32 v32, 16, v78
	v_and_b32_e32 v33, 0xffff0000, v78
	v_pk_add_f32 v[30:31], v[30:31], v[34:35]
	v_pk_add_f32 v[32:33], v[24:25], v[32:33]
	v_cvt_pk_bf16_f32 v24, v28, v29
	v_mul_f32_e32 v29, v29, v29
	v_fmac_f32_e32 v29, v28, v28
	v_mul_f32_e32 v28, v31, v31
	v_fmac_f32_e32 v28, v30, v30
	v_lshlrev_b32_e32 v34, 16, v79
	v_and_b32_e32 v35, 0xffff0000, v79
	v_add_f32_e32 v28, v29, v28
	v_mul_f32_e32 v29, v33, v33
	v_pk_add_f32 v[34:35], v[26:27], v[34:35]
	v_fmac_f32_e32 v29, v32, v32
	v_add_f32_e32 v28, v29, v28
	v_mul_f32_e32 v29, v35, v35
	v_fmac_f32_e32 v29, v34, v34
	v_cvt_pk_bf16_f32 v25, v30, v31
	v_cvt_pk_bf16_f32 v26, v32, v33
	v_add_f32_e32 v32, v29, v28
	s_waitcnt vmcnt(6)
	v_lshlrev_b32_e32 v28, 16, v72
	v_and_b32_e32 v29, 0xffff0000, v72
	v_lshlrev_b32_e32 v30, 16, v73
	v_and_b32_e32 v31, 0xffff0000, v73
	v_pk_add_f32 v[22:23], v[22:23], v[30:31]
	v_pk_add_f32 v[20:21], v[20:21], v[28:29]
	v_lshlrev_b32_e32 v28, 16, v74
	v_and_b32_e32 v29, 0xffff0000, v74
	v_pk_add_f32 v[28:29], v[16:17], v[28:29]
	v_mul_f32_e32 v16, v21, v21
	v_mul_f32_e32 v17, v23, v23
	v_fmac_f32_e32 v16, v20, v20
	v_fmac_f32_e32 v17, v22, v22
	v_lshlrev_b32_e32 v30, 16, v75
	v_and_b32_e32 v31, 0xffff0000, v75
	v_add_f32_e32 v16, v16, v17
	v_mul_f32_e32 v17, v29, v29
	v_pk_add_f32 v[30:31], v[18:19], v[30:31]
	v_fmac_f32_e32 v17, v28, v28
	v_add_f32_e32 v16, v17, v16
	v_mul_f32_e32 v17, v31, v31
	v_fmac_f32_e32 v17, v30, v30
	v_add_f32_e32 v16, v17, v16
	v_add_f32_e32 v19, v32, v16
	v_cvt_pk_bf16_f32 v27, v34, v35
	ds_bpermute_b32 v34, v190, v19
	v_lshl_add_u64 v[16:17], s[16:17], 0, v[98:99]
	v_lshl_add_u64 v[32:33], v[166:167], 1, v[16:17]
	v_cvt_pk_bf16_f32 v18, v20, v21
	v_cvt_pk_bf16_f32 v20, v28, v29
	s_waitcnt lgkmcnt(0)
	v_add_f32_e32 v16, v19, v34
	ds_bpermute_b32 v17, v189, v16
	v_cvt_pk_bf16_f32 v19, v22, v23
	v_cvt_pk_bf16_f32 v21, v30, v31
	global_store_dwordx4 v[32:33], v[24:27], off
	global_store_dwordx4 v[32:33], v[18:21], off offset:256
	s_and_saveexec_b64 s[40:41], s[36:37]
	s_cbranch_execz .LBB0_116
	s_waitcnt lgkmcnt(0)
	v_add_f32_e32 v18, v16, v17
	v_lshlrev_b64 v[16:17], 6, v[96:97]
	s_lshl_b32 s42, s26, 2
	v_lshl_add_u64 v[16:17], s[10:11], 0, v[16:17]
	s_ashr_i32 s43, s42, 31
	v_lshl_add_u64 v[16:17], s[42:43], 2, v[16:17]
	s_lshl_b32 s42, s77, 2
	s_mov_b32 s43, s4
	v_lshl_add_u64 v[16:17], v[16:17], 0, s[42:43]
	global_store_dword v[16:17], v18, off
